# diff attention loop: running-max chain moved to the head of the PV MFMA block (temps in free registers), 16 in-place score rescales moved from the post-barrier VALU interval into the PV block
# speedup vs baseline: 1.0060x; 1.0057x over previous
; #define SBAR() __builtin_amdgcn_sched_barrier(0)
; #define SLOAD(i, j) do { const long rb_ = KROW(j); sr_[i].vs0 = *(const bf16x8*)(a.V + (rb_ + sr) * LDV + sc); sr_[i].vs1 = *(const bf16x8*)(a.V + (rb_ + 32 + sr) * LDV + sc); \
;     _Pragma("unroll") for (int c_ = 0; c_ < KCH; ++c_) sr_[i].ks[c_] = *(const bf16x8*)(kptr[c_] + rb_ * kld[c_]); } while (0)
; __device__ __forceinline__ void partialSM(f32x16& p0, f32x16& p1, float& m_reg, float& mn, float& alpha, const float C, const float thr) {
;     float pmax = p0[0];
; #pragma unroll
;     for (int r = 1; r < 16; ++r) pmax = fmaxf(pmax, p0[r]);
; #pragma unroll
;     for (int r = 0; r < 16; ++r) pmax = fmaxf(pmax, p1[r]);
;     { auto rr = __builtin_amdgcn_permlane32_swap(__float_as_uint(pmax), __float_as_uint(pmax), false, false);
;       pmax = fmaxf(__uint_as_float(rr[0]), __uint_as_float(rr[1])); }
; template <int DQK, int DK1, int LDQ, int LDK, int LDKR, int LDV, int NQL, int SDEPTH>
; __device__ __forceinline__ void attn_core(const AttnArgs& a, char* lds, f32x16 (&o)[4]) {
;     ...
;     for (int j = 1; j + 1 < NT; j += 2) {
;         SBAR(); QKT(pB0, pB1, K_lds + SHM_K);
;         finishSM(pA0, pA1, alA, l_reg, pa0, pa1, pa2, pa3); SBAR();
;         SLOAD(SO, j + SDEPTH); SBAR();
;         pv_d0(o, vb0, pa0, pa1, pa2, pa3); partialSM(pB0, pB1, m_reg, mnB, alB, a.C, a.thr);
.LBB0_171:
	s_add_i32 s37, s52, -3
	ds_read_b128 v[64:67], v186 offset:40960
	ds_read_b128 v[68:71], v186 offset:45056
	v_exp_f32_e32 v143, v138
	v_add_f32_e32 v138, 0, v217
	v_add_f32_e32 v138, v219, v138
	s_waitcnt lgkmcnt(1)
	v_mfma_f32_32x32x16_bf16 v[80:95], v[64:67], v[110:113], 0
	v_add_f32_e32 v138, v208, v138
	v_add_f32_e32 v138, v218, v138
	v_add_f32_e32 v138, v153, v138
	ds_read_b128 v[204:207], v188 offset:40960
	ds_read_b128 v[220:223], v188 offset:45056
	v_add_f32_e32 v138, v216, v138
	v_add_f32_e32 v138, v152, v138
	v_add_f32_e32 v138, v202, v138
	s_waitcnt lgkmcnt(2)
	v_mfma_f32_32x32x16_bf16 v[64:79], v[68:71], v[110:113], 0
	v_add_f32_e32 v138, v149, v138
	v_add_f32_e32 v138, v151, v138
	v_add_f32_e32 v138, v147, v138
	v_add_f32_e32 v138, v150, v138
	v_add_f32_e32 v138, v145, v138
	v_exp_f32_e32 v191, v139
	v_add_f32_e32 v138, v148, v138
	s_waitcnt lgkmcnt(1)
	v_mfma_f32_32x32x16_bf16 v[80:95], v[204:207], v[106:109], v[80:95]
	v_exp_f32_e32 v136, v136
	v_add_f32_e32 v138, v144, v138
	v_exp_f32_e32 v137, v137
	v_add_f32_e32 v138, v146, v138
	v_exp_f32_e32 v130, v130
	v_add_f32_e32 v138, v143, v138
	v_exp_f32_e32 v131, v131
	s_waitcnt lgkmcnt(0)
	v_mfma_f32_32x32x16_bf16 v[64:79], v[220:223], v[106:109], v[64:79]
	ds_read_b128 v[204:207], v190 offset:40960
	ds_read_b128 v[220:223], v190 offset:45056
	v_add_f32_e32 v138, v191, v138
	v_exp_f32_e32 v128, v128
	v_add_f32_e32 v138, v136, v138
	v_exp_f32_e32 v129, v129
	v_add_f32_e32 v138, v137, v138
	v_exp_f32_e32 v126, v126
	s_waitcnt lgkmcnt(1)
	v_mfma_f32_32x32x16_bf16 v[80:95], v[204:207], v[102:105], v[80:95]
	v_add_f32_e32 v138, v130, v138
	v_exp_f32_e32 v127, v127
	v_add_f32_e32 v138, v131, v138
	v_exp_f32_e32 v200, v140
	v_add_f32_e32 v138, v128, v138
	v_exp_f32_e32 v210, v141
	v_add_f32_e32 v138, v129, v138
	s_waitcnt lgkmcnt(0)
	v_mfma_f32_32x32x16_bf16 v[64:79], v[220:223], v[102:105], v[64:79]
	ds_read_b128 v[204:207], v192 offset:40960
	ds_read_b128 v[220:223], v192 offset:45056
	v_exp_f32_e32 v134, v134
	v_add_f32_e32 v138, v126, v138
	v_exp_f32_e32 v135, v135
	v_add_f32_e32 v138, v127, v138
	v_exp_f32_e32 v132, v132
	v_add_f32_e32 v138, v200, v138
	s_waitcnt lgkmcnt(1)
	v_mfma_f32_32x32x16_bf16 v[80:95], v[204:207], v[98:101], v[80:95]
	v_exp_f32_e32 v133, v133
	v_add_f32_e32 v138, v210, v138
	v_add_f32_e32 v138, v134, v138
	v_add_f32_e32 v138, v135, v138
	v_add_f32_e32 v138, v132, v138
	v_add_f32_e32 v196, v133, v138
	v_mov_b32_e32 v198, v196
	s_waitcnt lgkmcnt(0)
	v_mfma_f32_32x32x16_bf16 v[64:79], v[220:223], v[98:101], v[64:79]
	v_cvt_pk_bf16_f32 v138, v217, v219
	v_cvt_pk_bf16_f32 v139, v208, v218
	v_cvt_pk_bf16_f32 v140, v153, v216
	v_permlane32_swap_b32_e32 v196, v198
	v_cvt_pk_bf16_f32 v141, v152, v202
	v_permlane32_swap_b32_e32 v138, v140
	v_cvt_pk_bf16_f32 v204, v149, v151
	v_cvt_pk_bf16_f32 v205, v147, v150
	v_cvt_pk_bf16_f32 v206, v145, v148
	v_cvt_pk_bf16_f32 v207, v144, v146
	v_cvt_pk_bf16_f32 v144, v143, v191
	v_cvt_pk_bf16_f32 v145, v136, v137
	v_cvt_pk_bf16_f32 v146, v130, v131
	v_cvt_pk_bf16_f32 v147, v128, v129
	v_cvt_pk_bf16_f32 v148, v126, v127
	v_cvt_pk_bf16_f32 v149, v200, v210
	v_cvt_pk_bf16_f32 v150, v134, v135
	v_cvt_pk_bf16_f32 v151, v132, v133
	v_permlane32_swap_b32_e32 v139, v141
	v_permlane32_swap_b32_e32 v204, v206
	v_permlane32_swap_b32_e32 v205, v207
	v_permlane32_swap_b32_e32 v144, v146
	v_permlane32_swap_b32_e32 v145, v147
	v_permlane32_swap_b32_e32 v148, v150
	v_permlane32_swap_b32_e32 v149, v151
	s_cmp_lt_u32 s37, 30
	s_cselect_b32 s14, 0, 0xffffffe0
	s_cselect_b32 s15, s18, s86
	s_add_i32 s14, s14, s52
	s_lshl_b32 s14, s14, 6
	s_add_i32 s14, s14, s15
	s_sub_i32 s14, s14, 64
	s_ashr_i32 s15, s14, 31
	v_lshl_add_u64 v[126:127], s[14:15], 0, v[164:165]
	v_lshl_add_u64 v[130:131], v[168:169], 0, s[14:15]
	v_mad_u64_u32 v[128:129], s[38:39], v126, s9, v[170:171]
	v_mad_u64_u32 v[132:133], s[38:39], v130, s9, v[170:171]
	v_mad_i32_i24 v129, v127, s9, v129
	v_mad_i32_i24 v133, v131, s9, v133
	v_mad_i64_i32 v[134:135], s[14:15], s14, v195, v[166:167]
	global_load_dwordx4 v[126:129], v[128:129], off
	s_nop 0
	global_load_dwordx4 v[130:133], v[132:133], off
	s_nop 0
	global_load_dwordx4 v[134:137], v[134:135], off
	ds_read_b64_tr_b16 v[216:217], v180 offset:0
	ds_read_b64_tr_b16 v[218:219], v180 offset:0x800
	ds_read_b64_tr_b16 v[220:221], v180 offset:0x1000
	ds_read_b64_tr_b16 v[222:223], v180 offset:0x1800
	ds_read_b64_tr_b16 v[224:225], v180 offset:0x2000
	ds_read_b64_tr_b16 v[226:227], v180 offset:0x2800
	ds_read_b64_tr_b16 v[228:229], v180 offset:0x3000
	ds_read_b64_tr_b16 v[230:231], v180 offset:0x3800
	s_waitcnt lgkmcnt(0)
	s_nop 0
	v_mfma_f32_32x32x16_bf16 v[48:63], v[138:141], v[216:219], v[48:63]
	ds_read_b64_tr_b16 v[216:217], v180 offset:0x200
	ds_read_b64_tr_b16 v[218:219], v180 offset:0xa00
	v_max_f32_e32 v238, v81, v81
	v_max_f32_e32 v239, v80, v80
	v_max_f32_e32 v238, v239, v238
	v_max3_f32 v238, v238, v82, v83
	v_max3_f32 v238, v238, v84, v85
	v_max3_f32 v238, v238, v86, v87
	v_mfma_f32_32x32x16_bf16 v[48:63], v[204:207], v[220:223], v[48:63]
	ds_read_b64_tr_b16 v[220:221], v180 offset:0x1200
	ds_read_b64_tr_b16 v[222:223], v180 offset:0x1a00
	v_max3_f32 v238, v238, v88, v89
	v_max3_f32 v238, v238, v90, v91
	v_max3_f32 v238, v238, v92, v93
	v_max3_f32 v238, v238, v94, v95
	v_max3_f32 v238, v238, v64, v65
	v_max3_f32 v238, v238, v66, v67
	v_mfma_f32_32x32x16_bf16 v[48:63], v[144:147], v[224:227], v[48:63]
	ds_read_b64_tr_b16 v[224:225], v180 offset:0x2200
	ds_read_b64_tr_b16 v[226:227], v180 offset:0x2a00
	v_max3_f32 v238, v238, v68, v69
	v_max3_f32 v238, v238, v70, v71
	v_max3_f32 v238, v238, v72, v73
	v_max3_f32 v238, v238, v74, v75
	v_max3_f32 v238, v238, v76, v77
	v_max3_f32 v238, v238, v78, v79
	v_mfma_f32_32x32x16_bf16 v[48:63], v[148:151], v[228:231], v[48:63]
	ds_read_b64_tr_b16 v[228:229], v180 offset:0x3200
	ds_read_b64_tr_b16 v[230:231], v180 offset:0x3a00
	v_mov_b32_e32 v239, v238
	s_nop 1
	v_permlane32_swap_b32_e32 v238, v239
	v_max_f32_e32 v239, v239, v239
	v_max_f32_e32 v238, v238, v238
	v_max_f32_e32 v238, v238, v239
	s_waitcnt lgkmcnt(0)
; #define SBAR() __builtin_amdgcn_sched_barrier(0)
; template <int OFF> __device__ __forceinline__ s16x4 tr_read(int vb) { s16x4 r; asm volatile("ds_read_b64_tr_b16 %0, %1 offset:%2" : "=&v"(r) : "v"(vb), "i"(OFF) : "memory"); return r; }
; #define SWRITE(b, i) do { *(bf16x8*)(V_lds + (b) * SHM_V + vst0) = sr_[i].vs0; *(bf16x8*)(V_lds + (b) * SHM_V + vst1) = sr_[i].vs1; \
;     _Pragma("unroll") for (int c_ = 0; c_ < KCH; ++c_) *(bf16x8*)(K_lds + (b) * SHM_K + kwo[c_]) = sr_[i].ks[c_]; } while (0)
; template <int D0> __device__ __forceinline__ void pv_one(f32x16& od, int vb, bf16x8 pa0, bf16x8 pa1, bf16x8 pa2, bf16x8 pa3) {
;     const s16x4 l0 = tr_read<v_rd_off(D0, 0, 0)>(vb), h0 = tr_read<v_rd_off(D0, 0, 1)>(vb), l1 = tr_read<v_rd_off(D0, 1, 0)>(vb), h1 = tr_read<v_rd_off(D0, 1, 1)>(vb);
;     const s16x4 l2 = tr_read<v_rd_off(D0, 2, 0)>(vb), h2 = tr_read<v_rd_off(D0, 2, 1)>(vb), l3 = tr_read<v_rd_off(D0, 3, 0)>(vb), h3 = tr_read<v_rd_off(D0, 3, 1)>(vb);
;     asm volatile("s_waitcnt lgkmcnt(0)" ::: "memory"); SBAR();
;     ...
;     od = __builtin_amdgcn_mfma_f32_32x32x16_bf16(pa0, PK(l0, h0), od, 0, 0, 0);
;     od = __builtin_amdgcn_mfma_f32_32x32x16_bf16(pa1, PK(l1, h1), od, 0, 0, 0);
;     od = __builtin_amdgcn_mfma_f32_32x32x16_bf16(pa2, PK(l2, h2), od, 0, 0, 0);
;     od = __builtin_amdgcn_mfma_f32_32x32x16_bf16(pa3, PK(l3, h3), od, 0, 0, 0);
;     ...
; }
; __device__ __forceinline__ void pv_d0(f32x16* o, int vb, bf16x8 pa0, bf16x8 pa1, bf16x8 pa2, bf16x8 pa3) {
;     pv_one<0>(o[0], vb, pa0, pa1, pa2, pa3); pv_one<1>(o[1], vb, pa0, pa1, pa2, pa3); pv_one<2>(o[2], vb, pa0, pa1, pa2, pa3); pv_one<3>(o[3], vb, pa0, pa1, pa2, pa3);
; __device__ __forceinline__ void partialSM(f32x16& p0, f32x16& p1, float& m_reg, float& mn, float& alpha, const float C, const float thr) {
;     ...
;     if (__builtin_expect(__all(pmax - m_reg <= thr), 1)) { mn = m_reg; alpha = 1.f; }
;     else { mn = fmaxf(m_reg, pmax); alpha = __builtin_amdgcn_exp2f((m_reg - mn) * C); m_reg = mn; }
;     const float mnC = -mn * C;
; #pragma unroll
;     for (int r = 0; r < 16; ++r) p0[r] = fmaf(p0[r], C, mnC);
; template <int DQK, int DK1, int LDQ, int LDK, int LDKR, int LDV, int NQL, int SDEPTH>
; __device__ __forceinline__ void attn_core(const AttnArgs& a, char* lds, f32x16 (&o)[4]) {
;     ...
;         __syncthreads(); SWRITE(0, SE);
;         RESC(alB); __syncthreads();
	v_mfma_f32_32x32x16_bf16 v[32:47], v[138:141], v[216:219], v[32:47]
	ds_read_b64_tr_b16 v[216:217], v180 offset:0x400
	ds_read_b64_tr_b16 v[218:219], v180 offset:0xc00
	v_sub_f32_e32 v239, v238, v142
	v_cmp_ge_f32_e32 vcc, s76, v239
	v_max_f32_e32 v239, v142, v142
	v_max_f32_e32 v238, v239, v238
	v_sub_f32_e32 v239, v142, v238
	v_mul_f32_e32 v239, 0x3e38aa3b, v239
	v_mfma_f32_32x32x16_bf16 v[32:47], v[204:207], v[220:223], v[32:47]
	ds_read_b64_tr_b16 v[220:221], v180 offset:0x1400
	ds_read_b64_tr_b16 v[222:223], v180 offset:0x1c00
	v_exp_f32_e32 v239, v239
	s_cmp_eq_u64 vcc, exec
	s_cselect_b64 s[14:15], -1, 0
	v_cndmask_b32_e64 v200, v239, 1.0, s[14:15]
	v_cmp_gt_f32_e32 vcc, 1.0, v200
	v_mfma_f32_32x32x16_bf16 v[32:47], v[144:147], v[224:227], v[32:47]
	ds_read_b64_tr_b16 v[224:225], v180 offset:0x2400
	ds_read_b64_tr_b16 v[226:227], v180 offset:0x2c00
	v_cndmask_b32_e64 v241, v238, v142, s[14:15]
	v_mul_f32_e32 v239, 0xbe38aa3b, v241
	v_fmamk_f32 v80, v80, 0x3e38aa3b, v239
	v_fmamk_f32 v81, v81, 0x3e38aa3b, v239
	v_mfma_f32_32x32x16_bf16 v[32:47], v[148:151], v[228:231], v[32:47]
	ds_read_b64_tr_b16 v[228:229], v180 offset:0x3400
	ds_read_b64_tr_b16 v[230:231], v180 offset:0x3c00
	v_fmamk_f32 v82, v82, 0x3e38aa3b, v239
	v_fmamk_f32 v83, v83, 0x3e38aa3b, v239
	v_fmamk_f32 v84, v84, 0x3e38aa3b, v239
	v_fmamk_f32 v85, v85, 0x3e38aa3b, v239
	s_waitcnt lgkmcnt(0)
	v_mfma_f32_32x32x16_bf16 v[16:31], v[138:141], v[216:219], v[16:31]
	ds_read_b64_tr_b16 v[216:217], v180 offset:0x600
	ds_read_b64_tr_b16 v[218:219], v180 offset:0xe00
	v_fmamk_f32 v86, v86, 0x3e38aa3b, v239
	v_fmamk_f32 v87, v87, 0x3e38aa3b, v239
	v_fmamk_f32 v88, v88, 0x3e38aa3b, v239
	v_fmamk_f32 v89, v89, 0x3e38aa3b, v239
	v_mfma_f32_32x32x16_bf16 v[16:31], v[204:207], v[220:223], v[16:31]
	ds_read_b64_tr_b16 v[220:221], v180 offset:0x1600
	ds_read_b64_tr_b16 v[222:223], v180 offset:0x1e00
	v_fmamk_f32 v90, v90, 0x3e38aa3b, v239
	v_fmamk_f32 v91, v91, 0x3e38aa3b, v239
	v_fmamk_f32 v92, v92, 0x3e38aa3b, v239
	v_fmamk_f32 v93, v93, 0x3e38aa3b, v239
	v_mfma_f32_32x32x16_bf16 v[16:31], v[144:147], v[224:227], v[16:31]
	ds_read_b64_tr_b16 v[224:225], v180 offset:0x2600
	ds_read_b64_tr_b16 v[226:227], v180 offset:0x2e00
	v_fmamk_f32 v94, v94, 0x3e38aa3b, v239
	v_fmamk_f32 v95, v95, 0x3e38aa3b, v239
	v_mfma_f32_32x32x16_bf16 v[16:31], v[148:151], v[228:231], v[16:31]
	ds_read_b64_tr_b16 v[228:229], v180 offset:0x3600
	ds_read_b64_tr_b16 v[230:231], v180 offset:0x3e00
	s_waitcnt lgkmcnt(0)
	v_mfma_f32_32x32x16_bf16 v[0:15], v[138:141], v[216:219], v[0:15]
	v_mfma_f32_32x32x16_bf16 v[0:15], v[204:207], v[220:223], v[0:15]
	v_mfma_f32_32x32x16_bf16 v[0:15], v[144:147], v[224:227], v[0:15]
	v_mfma_f32_32x32x16_bf16 v[0:15], v[148:151], v[228:231], v[0:15]
	s_barrier
	s_waitcnt vmcnt(5)
	ds_write_b128 v181, v[114:117]
	s_waitcnt vmcnt(4)
	ds_write_b128 v184, v[118:121]
	s_waitcnt vmcnt(3)
	ds_write_b128 v182, v[122:125] offset:32768
	s_cbranch_vccz .LBB0_175
	s_and_saveexec_b64 s[38:39], s[12:13]
	ds_write_b32 v177, v200 offset:49280
	s_or_b64 exec, exec, s[38:39]
	s_waitcnt lgkmcnt(0)
	v_add_u32_e32 v139, v161, v96
	ds_read_b128 v[144:147], v139 offset:49376
	ds_read_b128 v[148:151], v139 offset:49344
	ds_read_b128 v[204:207], v139 offset:49312
	ds_read_b128 v[216:219], v139 offset:49280
	s_waitcnt lgkmcnt(3)
	v_pk_mul_f32 v[60:61], v[60:61], v[144:145]
	s_waitcnt lgkmcnt(2)
	v_pk_mul_f32 v[56:57], v[56:57], v[148:149]
	s_waitcnt lgkmcnt(1)
	v_pk_mul_f32 v[52:53], v[52:53], v[204:205]
	v_pk_mul_f32 v[62:63], v[62:63], v[146:147]
	v_pk_mul_f32 v[58:59], v[58:59], v[150:151]
	v_pk_mul_f32 v[54:55], v[54:55], v[206:207]
	s_waitcnt lgkmcnt(0)
	v_pk_mul_f32 v[50:51], v[50:51], v[218:219]
	v_pk_mul_f32 v[48:49], v[48:49], v[216:217]
	v_pk_mul_f32 v[44:45], v[44:45], v[144:145]
	v_pk_mul_f32 v[40:41], v[40:41], v[148:149]
	v_pk_mul_f32 v[36:37], v[36:37], v[204:205]
	v_pk_mul_f32 v[46:47], v[46:47], v[146:147]
	v_pk_mul_f32 v[42:43], v[42:43], v[150:151]
	v_pk_mul_f32 v[38:39], v[38:39], v[206:207]
	v_pk_mul_f32 v[34:35], v[34:35], v[218:219]
	v_pk_mul_f32 v[32:33], v[32:33], v[216:217]
	v_pk_mul_f32 v[28:29], v[28:29], v[144:145]
	v_pk_mul_f32 v[24:25], v[24:25], v[148:149]
	v_pk_mul_f32 v[20:21], v[20:21], v[204:205]
	v_pk_mul_f32 v[30:31], v[30:31], v[146:147]
	v_pk_mul_f32 v[26:27], v[26:27], v[150:151]
	v_pk_mul_f32 v[22:23], v[22:23], v[206:207]
	v_pk_mul_f32 v[18:19], v[18:19], v[218:219]
	v_pk_mul_f32 v[16:17], v[16:17], v[216:217]
	v_pk_mul_f32 v[12:13], v[12:13], v[144:145]
	v_pk_mul_f32 v[8:9], v[8:9], v[148:149]
	v_pk_mul_f32 v[4:5], v[4:5], v[204:205]
	v_pk_mul_f32 v[14:15], v[14:15], v[146:147]
	v_pk_mul_f32 v[10:11], v[10:11], v[150:151]
	v_pk_mul_f32 v[6:7], v[6:7], v[206:207]
	v_pk_mul_f32 v[2:3], v[2:3], v[218:219]
	v_pk_mul_f32 v[0:1], v[0:1], v[216:217]
; __device__ __forceinline__ void partialSM(f32x16& p0, f32x16& p1, float& m_reg, float& mn, float& alpha, const float C, const float thr) {
;     ...
;     const float mnC = -mn * C;
; #pragma unroll
;     for (int r = 0; r < 16; ++r) p0[r] = fmaf(p0[r], C, mnC);
; #pragma unroll
;     for (int r = 0; r < 16; ++r) p1[r] = fmaf(p1[r], C, mnC);
; #pragma unroll
;     for (int r = 0; r < 16; ++r) p0[r] = __builtin_amdgcn_exp2f(p0[r]);
; }
; __device__ __forceinline__ void finishSM(f32x16& p0, f32x16& p1, float alpha, float& l_reg, bf16x8& pa0, bf16x8& pa1, bf16x8& pa2, bf16x8& pa3) {
; #pragma unroll
;     for (int r = 0; r < 16; ++r) p1[r] = __builtin_amdgcn_exp2f(p1[r]);
;     float ps = 0;
; #pragma unroll
;     for (int r = 0; r < 16; ++r) ps += p0[r];
; #pragma unroll
;     for (int r = 0; r < 16; ++r) ps += p1[r];
;     { auto rr = __builtin_amdgcn_permlane32_swap(__float_as_uint(ps), __float_as_uint(ps), false, false);
;       ps = __uint_as_float(rr[0]) + __uint_as_float(rr[1]); }
;     l_reg = l_reg * alpha + ps;
;     ...
;     PK4(p0, 0, pa0); PK4(p0, 8, pa1); PK4(p1, 0, pa2); PK4(p1, 8, pa3);
.LBB0_175:
	v_cndmask_b32_e64 v202, v238, v142, s[14:15]
	v_mul_f32_e32 v204, 0xbe38aa3b, v202
	v_exp_f32_e32 v138, v80
	v_exp_f32_e32 v153, v81
	v_exp_f32_e32 v139, v82
	v_exp_f32_e32 v152, v83
	v_exp_f32_e32 v140, v84
	v_exp_f32_e32 v151, v85
	v_exp_f32_e32 v141, v86
	v_exp_f32_e32 v150, v87
	v_exp_f32_e32 v142, v88
	v_exp_f32_e32 v149, v89
	v_exp_f32_e32 v143, v90
	v_exp_f32_e32 v148, v91
	v_exp_f32_e32 v144, v92
	v_exp_f32_e32 v147, v93
	v_exp_f32_e32 v145, v94
	v_exp_f32_e32 v146, v95
	v_fmamk_f32 v222, v64, 0x3e38aa3b, v204
	v_fmamk_f32 v223, v65, 0x3e38aa3b, v204
	v_fmamk_f32 v224, v66, 0x3e38aa3b, v204
	v_fmamk_f32 v225, v67, 0x3e38aa3b, v204
	v_fmamk_f32 v226, v68, 0x3e38aa3b, v204
	v_fmamk_f32 v208, v69, 0x3e38aa3b, v204
	v_fmamk_f32 v216, v70, 0x3e38aa3b, v204
	v_fmamk_f32 v217, v71, 0x3e38aa3b, v204
	v_fmamk_f32 v218, v72, 0x3e38aa3b, v204
	v_fmamk_f32 v219, v73, 0x3e38aa3b, v204
	v_fmamk_f32 v220, v74, 0x3e38aa3b, v204
	v_fmamk_f32 v221, v75, 0x3e38aa3b, v204
	v_fmamk_f32 v206, v76, 0x3e38aa3b, v204
	v_fmamk_f32 v227, v77, 0x3e38aa3b, v204
	v_fmamk_f32 v228, v78, 0x3e38aa3b, v204
	v_fmac_f32_e32 v204, 0x3e38aa3b, v79
	s_waitcnt lgkmcnt(0)
	s_barrier
	ds_read_b128 v[64:67], v186 offset:32768
	ds_read_b128 v[68:71], v186 offset:36864
	v_exp_f32_e32 v205, v223
	v_exp_f32_e32 v223, v204
	v_add_f32_e32 v204, 0, v138
	v_add_f32_e32 v204, v153, v204
	s_waitcnt lgkmcnt(1)
	v_mfma_f32_32x32x16_bf16 v[80:95], v[64:67], v[110:113], 0
	v_add_f32_e32 v204, v139, v204
	v_add_f32_e32 v204, v152, v204
	v_add_f32_e32 v204, v140, v204
	ds_read_b128 v[230:233], v188 offset:32768
	ds_read_b128 v[234:237], v188 offset:36864
	v_add_f32_e32 v204, v151, v204
	v_add_f32_e32 v204, v141, v204
	v_add_f32_e32 v204, v150, v204
	s_waitcnt lgkmcnt(2)
	v_mfma_f32_32x32x16_bf16 v[64:79], v[68:71], v[110:113], 0
	v_add_f32_e32 v204, v142, v204
	v_add_f32_e32 v204, v149, v204
	v_add_f32_e32 v204, v143, v204
	v_add_f32_e32 v204, v148, v204
	v_exp_f32_e32 v191, v222
	v_add_f32_e32 v204, v144, v204
	v_add_f32_e32 v204, v147, v204
	s_waitcnt lgkmcnt(1)
	v_mfma_f32_32x32x16_bf16 v[80:95], v[230:233], v[106:109], v[80:95]
	v_exp_f32_e32 v207, v224
	v_add_f32_e32 v204, v145, v204
	v_exp_f32_e32 v210, v225
	v_add_f32_e32 v204, v146, v204
	v_exp_f32_e32 v211, v226
	v_add_f32_e32 v204, v191, v204
	v_exp_f32_e32 v208, v208
	s_waitcnt lgkmcnt(0)
	v_mfma_f32_32x32x16_bf16 v[64:79], v[234:237], v[106:109], v[64:79]
	ds_read_b128 v[230:233], v190 offset:32768
	ds_read_b128 v[234:237], v190 offset:36864
	v_add_f32_e32 v204, v205, v204
	v_exp_f32_e32 v212, v216
	v_add_f32_e32 v204, v207, v204
	v_exp_f32_e32 v213, v217
	v_add_f32_e32 v204, v210, v204
	v_exp_f32_e32 v216, v218
	s_waitcnt lgkmcnt(1)
	v_mfma_f32_32x32x16_bf16 v[80:95], v[230:233], v[102:105], v[80:95]
	v_add_f32_e32 v204, v211, v204
	v_exp_f32_e32 v217, v219
	v_add_f32_e32 v204, v208, v204
	v_exp_f32_e32 v218, v220
	v_add_f32_e32 v204, v212, v204
	v_exp_f32_e32 v219, v221
	v_add_f32_e32 v204, v213, v204
	s_waitcnt lgkmcnt(0)
	v_mfma_f32_32x32x16_bf16 v[64:79], v[234:237], v[102:105], v[64:79]
	ds_read_b128 v[230:233], v192 offset:32768
	ds_read_b128 v[234:237], v192 offset:36864
	v_exp_f32_e32 v220, v206
	v_add_f32_e32 v204, v216, v204
	v_exp_f32_e32 v221, v227
	v_add_f32_e32 v204, v217, v204
	v_exp_f32_e32 v222, v228
	v_add_f32_e32 v204, v218, v204
	s_waitcnt lgkmcnt(1)
	v_mfma_f32_32x32x16_bf16 v[80:95], v[230:233], v[98:101], v[80:95]
	v_add_f32_e32 v204, v219, v204
	v_add_f32_e32 v204, v220, v204
	v_add_f32_e32 v204, v221, v204
	v_add_f32_e32 v204, v222, v204
	v_add_f32_e32 v204, v223, v204
	v_mov_b32_e32 v206, v204
	v_cvt_pk_bf16_f32 v138, v138, v153
	s_waitcnt lgkmcnt(0)
	v_mfma_f32_32x32x16_bf16 v[64:79], v[234:237], v[98:101], v[64:79]
	v_cvt_pk_bf16_f32 v139, v139, v152
	v_cvt_pk_bf16_f32 v140, v140, v151
	v_cvt_pk_bf16_f32 v141, v141, v150
	v_cvt_pk_bf16_f32 v142, v142, v149
	v_cvt_pk_bf16_f32 v143, v143, v148
	v_cvt_pk_bf16_f32 v144, v144, v147
	v_cvt_pk_bf16_f32 v145, v145, v146
	v_cvt_pk_bf16_f32 v146, v191, v205
	v_cvt_pk_bf16_f32 v147, v207, v210
	v_cvt_pk_bf16_f32 v148, v211, v208
	v_cvt_pk_bf16_f32 v149, v212, v213
	v_cvt_pk_bf16_f32 v150, v216, v217
	v_cvt_pk_bf16_f32 v151, v218, v219
	v_cvt_pk_bf16_f32 v152, v220, v221
	v_cvt_pk_bf16_f32 v153, v222, v223
	v_permlane32_swap_b32_e32 v204, v206
	v_permlane32_swap_b32_e32 v138, v140
	v_permlane32_swap_b32_e32 v139, v141
	v_permlane32_swap_b32_e32 v142, v144
	v_permlane32_swap_b32_e32 v143, v145
	v_permlane32_swap_b32_e32 v146, v148
	v_permlane32_swap_b32_e32 v147, v149
	v_permlane32_swap_b32_e32 v150, v152
	v_permlane32_swap_b32_e32 v151, v153
	s_cmp_gt_u32 s37, 32
	s_cbranch_scc1 .LBB0_177
	s_cmp_lt_u32 s37, 29
	s_cselect_b32 s14, 0, 0xffffffe0
	s_cselect_b32 s15, s18, s86
	s_add_i32 s14, s14, s52
	s_lshl_b32 s14, s14, 6
	s_add_i32 s14, s14, s15
	s_ashr_i32 s15, s14, 31
	v_lshl_add_u64 v[114:115], s[14:15], 0, v[164:165]
	v_lshl_add_u64 v[118:119], v[168:169], 0, s[14:15]
	v_mad_u64_u32 v[116:117], s[38:39], v114, s9, v[170:171]
	v_mad_u64_u32 v[120:121], s[38:39], v118, s9, v[170:171]
	v_mad_i32_i24 v117, v115, s9, v117
	v_mad_i32_i24 v121, v119, s9, v121
	v_mad_i64_i32 v[122:123], s[14:15], s14, v195, v[166:167]
	global_load_dwordx4 v[114:117], v[116:117], off
	s_nop 0
	global_load_dwordx4 v[118:121], v[120:121], off
	s_nop 0
	global_load_dwordx4 v[122:125], v[122:123], off
; #define SBAR() __builtin_amdgcn_sched_barrier(0)
; template <int OFF> __device__ __forceinline__ s16x4 tr_read(int vb) { s16x4 r; asm volatile("ds_read_b64_tr_b16 %0, %1 offset:%2" : "=&v"(r) : "v"(vb), "i"(OFF) : "memory"); return r; }
; template <int D0> __device__ __forceinline__ void pv_one(f32x16& od, int vb, bf16x8 pa0, bf16x8 pa1, bf16x8 pa2, bf16x8 pa3) {
;     const s16x4 l0 = tr_read<v_rd_off(D0, 0, 0)>(vb), h0 = tr_read<v_rd_off(D0, 0, 1)>(vb), l1 = tr_read<v_rd_off(D0, 1, 0)>(vb), h1 = tr_read<v_rd_off(D0, 1, 1)>(vb);
;     const s16x4 l2 = tr_read<v_rd_off(D0, 2, 0)>(vb), h2 = tr_read<v_rd_off(D0, 2, 1)>(vb), l3 = tr_read<v_rd_off(D0, 3, 0)>(vb), h3 = tr_read<v_rd_off(D0, 3, 1)>(vb);
;     asm volatile("s_waitcnt lgkmcnt(0)" ::: "memory"); SBAR();
;     ...
;     od = __builtin_amdgcn_mfma_f32_32x32x16_bf16(pa0, PK(l0, h0), od, 0, 0, 0);
;     od = __builtin_amdgcn_mfma_f32_32x32x16_bf16(pa1, PK(l1, h1), od, 0, 0, 0);
;     od = __builtin_amdgcn_mfma_f32_32x32x16_bf16(pa2, PK(l2, h2), od, 0, 0, 0);
;     od = __builtin_amdgcn_mfma_f32_32x32x16_bf16(pa3, PK(l3, h3), od, 0, 0, 0);
;     ...
; }
; __device__ __forceinline__ void pv_d0(f32x16* o, int vb, bf16x8 pa0, bf16x8 pa1, bf16x8 pa2, bf16x8 pa3) {
;     pv_one<0>(o[0], vb, pa0, pa1, pa2, pa3); pv_one<1>(o[1], vb, pa0, pa1, pa2, pa3); pv_one<2>(o[2], vb, pa0, pa1, pa2, pa3); pv_one<3>(o[3], vb, pa0, pa1, pa2, pa3);
; }
; __device__ __forceinline__ void partialSM(f32x16& p0, f32x16& p1, float& m_reg, float& mn, float& alpha, const float C, const float thr) {
;     float pmax = p0[0];
; #pragma unroll
;     for (int r = 1; r < 16; ++r) pmax = fmaxf(pmax, p0[r]);
; #pragma unroll
;     for (int r = 0; r < 16; ++r) pmax = fmaxf(pmax, p1[r]);
;     { auto rr = __builtin_amdgcn_permlane32_swap(__float_as_uint(pmax), __float_as_uint(pmax), false, false);
;       pmax = fmaxf(__uint_as_float(rr[0]), __uint_as_float(rr[1])); }
;     if (__builtin_expect(__all(pmax - m_reg <= thr), 1)) { mn = m_reg; alpha = 1.f; }
;     else { mn = fmaxf(m_reg, pmax); alpha = __builtin_amdgcn_exp2f((m_reg - mn) * C); m_reg = mn; }
;     const float mnC = -mn * C;
; #pragma unroll
;     for (int r = 0; r < 16; ++r) p0[r] = fmaf(p0[r], C, mnC);
; #pragma unroll
;     for (int r = 0; r < 16; ++r) p1[r] = fmaf(p1[r], C, mnC);
.LBB0_177:
	ds_read_b64_tr_b16 v[216:217], v179 offset:0
	ds_read_b64_tr_b16 v[218:219], v179 offset:0x800
	ds_read_b64_tr_b16 v[220:221], v179 offset:0x1000
	ds_read_b64_tr_b16 v[222:223], v179 offset:0x1800
	ds_read_b64_tr_b16 v[224:225], v179 offset:0x2000
	ds_read_b64_tr_b16 v[226:227], v179 offset:0x2800
	ds_read_b64_tr_b16 v[228:229], v179 offset:0x3000
	ds_read_b64_tr_b16 v[230:231], v179 offset:0x3800
	s_waitcnt lgkmcnt(0)
	s_nop 0
	v_mfma_f32_32x32x16_bf16 v[48:63], v[138:141], v[216:219], v[48:63]
	ds_read_b64_tr_b16 v[216:217], v179 offset:0x200
	ds_read_b64_tr_b16 v[218:219], v179 offset:0xa00
	v_max_f32_e32 v238, v81, v81
	v_max_f32_e32 v239, v80, v80
	v_max_f32_e32 v238, v239, v238
	v_max3_f32 v238, v238, v82, v83
	v_max3_f32 v238, v238, v84, v85
	v_max3_f32 v238, v238, v86, v87
	v_mfma_f32_32x32x16_bf16 v[48:63], v[142:145], v[220:223], v[48:63]
	ds_read_b64_tr_b16 v[220:221], v179 offset:0x1200
	ds_read_b64_tr_b16 v[222:223], v179 offset:0x1a00
	v_max3_f32 v238, v238, v88, v89
	v_max3_f32 v238, v238, v90, v91
	v_max3_f32 v238, v238, v92, v93
	v_max3_f32 v238, v238, v94, v95
	v_max3_f32 v238, v238, v64, v65
	v_max3_f32 v238, v238, v66, v67
	v_mfma_f32_32x32x16_bf16 v[48:63], v[146:149], v[224:227], v[48:63]
	ds_read_b64_tr_b16 v[224:225], v179 offset:0x2200
	ds_read_b64_tr_b16 v[226:227], v179 offset:0x2a00
	v_max3_f32 v238, v238, v68, v69
	v_max3_f32 v238, v238, v70, v71
	v_max3_f32 v238, v238, v72, v73
	v_max3_f32 v238, v238, v74, v75
	v_max3_f32 v238, v238, v76, v77
	v_max3_f32 v238, v238, v78, v79
	v_mfma_f32_32x32x16_bf16 v[48:63], v[150:153], v[228:231], v[48:63]
	ds_read_b64_tr_b16 v[228:229], v179 offset:0x3200
	ds_read_b64_tr_b16 v[230:231], v179 offset:0x3a00
	v_mov_b32_e32 v239, v238
	s_nop 1
	v_permlane32_swap_b32_e32 v238, v239
	v_max_f32_e32 v239, v239, v239
	v_max_f32_e32 v238, v238, v238
	v_max_f32_e32 v238, v238, v239
	s_waitcnt lgkmcnt(0)
	v_mfma_f32_32x32x16_bf16 v[32:47], v[138:141], v[216:219], v[32:47]
	ds_read_b64_tr_b16 v[216:217], v179 offset:0x400
	ds_read_b64_tr_b16 v[218:219], v179 offset:0xc00
	v_sub_f32_e32 v239, v238, v202
	v_cmp_ge_f32_e32 vcc, s76, v239
	v_max_f32_e32 v239, v202, v202
	v_max_f32_e32 v238, v239, v238
	v_sub_f32_e32 v239, v202, v238
	v_mul_f32_e32 v239, 0x3e38aa3b, v239
	v_mfma_f32_32x32x16_bf16 v[32:47], v[142:145], v[220:223], v[32:47]
	ds_read_b64_tr_b16 v[220:221], v179 offset:0x1400
	ds_read_b64_tr_b16 v[222:223], v179 offset:0x1c00
	v_exp_f32_e32 v239, v239
	s_cmp_eq_u64 vcc, exec
	s_cselect_b64 s[14:15], -1, 0
	v_cndmask_b32_e64 v240, v239, 1.0, s[14:15]
	v_cmp_gt_f32_e32 vcc, 1.0, v240
	v_mfma_f32_32x32x16_bf16 v[32:47], v[146:149], v[224:227], v[32:47]
	ds_read_b64_tr_b16 v[224:225], v179 offset:0x2400
	ds_read_b64_tr_b16 v[226:227], v179 offset:0x2c00
	v_cndmask_b32_e64 v241, v238, v202, s[14:15]
	v_mul_f32_e32 v239, 0xbe38aa3b, v241
	v_fmamk_f32 v80, v80, 0x3e38aa3b, v239
	v_fmamk_f32 v81, v81, 0x3e38aa3b, v239
	v_mfma_f32_32x32x16_bf16 v[32:47], v[150:153], v[228:231], v[32:47]
	ds_read_b64_tr_b16 v[228:229], v179 offset:0x3400
	ds_read_b64_tr_b16 v[230:231], v179 offset:0x3c00
	v_fmamk_f32 v82, v82, 0x3e38aa3b, v239
	v_fmamk_f32 v83, v83, 0x3e38aa3b, v239
	v_fmamk_f32 v84, v84, 0x3e38aa3b, v239
	v_fmamk_f32 v85, v85, 0x3e38aa3b, v239
	s_waitcnt lgkmcnt(0)
	v_mfma_f32_32x32x16_bf16 v[16:31], v[138:141], v[216:219], v[16:31]
	ds_read_b64_tr_b16 v[216:217], v179 offset:0x600
	ds_read_b64_tr_b16 v[218:219], v179 offset:0xe00
	v_fmamk_f32 v86, v86, 0x3e38aa3b, v239
	v_fmamk_f32 v87, v87, 0x3e38aa3b, v239
	v_fmamk_f32 v88, v88, 0x3e38aa3b, v239
	v_fmamk_f32 v89, v89, 0x3e38aa3b, v239
	v_mfma_f32_32x32x16_bf16 v[16:31], v[142:145], v[220:223], v[16:31]
	ds_read_b64_tr_b16 v[220:221], v179 offset:0x1600
	ds_read_b64_tr_b16 v[222:223], v179 offset:0x1e00
	v_fmamk_f32 v90, v90, 0x3e38aa3b, v239
	v_fmamk_f32 v91, v91, 0x3e38aa3b, v239
	v_fmamk_f32 v92, v92, 0x3e38aa3b, v239
	v_fmamk_f32 v93, v93, 0x3e38aa3b, v239
	v_mfma_f32_32x32x16_bf16 v[16:31], v[146:149], v[224:227], v[16:31]
	ds_read_b64_tr_b16 v[224:225], v179 offset:0x2600
	ds_read_b64_tr_b16 v[226:227], v179 offset:0x2e00
	v_fmamk_f32 v94, v94, 0x3e38aa3b, v239
	v_mfma_f32_32x32x16_bf16 v[16:31], v[150:153], v[228:231], v[16:31]
	ds_read_b64_tr_b16 v[228:229], v179 offset:0x3600
	ds_read_b64_tr_b16 v[230:231], v179 offset:0x3e00
	s_waitcnt lgkmcnt(0)
	v_mfma_f32_32x32x16_bf16 v[0:15], v[138:141], v[216:219], v[0:15]
	v_mfma_f32_32x32x16_bf16 v[0:15], v[142:145], v[220:223], v[0:15]
	v_mfma_f32_32x32x16_bf16 v[0:15], v[146:149], v[224:227], v[0:15]
	v_mfma_f32_32x32x16_bf16 v[0:15], v[150:153], v[228:231], v[0:15]
	v_mov_b32_e32 v143, v240
	s_barrier
	s_waitcnt vmcnt(2)
	ds_write_b128 v181, v[126:129] offset:16384
	s_waitcnt vmcnt(1)
	ds_write_b128 v184, v[130:133] offset:16384
	s_waitcnt vmcnt(0)
	ds_write_b128 v182, v[134:137] offset:40960
	s_cbranch_vccz .LBB0_181
	s_and_saveexec_b64 s[38:39], s[12:13]
	ds_write_b32 v177, v143 offset:49280
	s_or_b64 exec, exec, s[38:39]
	s_waitcnt lgkmcnt(0)
	v_add_u32_e32 v139, v161, v96
	ds_read_b128 v[126:129], v139 offset:49376
	ds_read_b128 v[130:133], v139 offset:49344
	ds_read_b128 v[134:137], v139 offset:49312
	ds_read_b128 v[144:147], v139 offset:49280
	s_waitcnt lgkmcnt(3)
	v_pk_mul_f32 v[60:61], v[60:61], v[126:127]
	s_waitcnt lgkmcnt(2)
	v_pk_mul_f32 v[56:57], v[56:57], v[130:131]
	s_waitcnt lgkmcnt(1)
	v_pk_mul_f32 v[52:53], v[52:53], v[134:135]
	v_pk_mul_f32 v[62:63], v[62:63], v[128:129]
	v_pk_mul_f32 v[58:59], v[58:59], v[132:133]
	v_pk_mul_f32 v[54:55], v[54:55], v[136:137]
	s_waitcnt lgkmcnt(0)
	v_pk_mul_f32 v[50:51], v[50:51], v[146:147]
	v_pk_mul_f32 v[48:49], v[48:49], v[144:145]
	v_pk_mul_f32 v[44:45], v[44:45], v[126:127]
	v_pk_mul_f32 v[40:41], v[40:41], v[130:131]
	v_pk_mul_f32 v[36:37], v[36:37], v[134:135]
	v_pk_mul_f32 v[46:47], v[46:47], v[128:129]
	v_pk_mul_f32 v[42:43], v[42:43], v[132:133]
	v_pk_mul_f32 v[38:39], v[38:39], v[136:137]
	v_pk_mul_f32 v[34:35], v[34:35], v[146:147]
	v_pk_mul_f32 v[32:33], v[32:33], v[144:145]
	v_pk_mul_f32 v[28:29], v[28:29], v[126:127]
	v_pk_mul_f32 v[24:25], v[24:25], v[130:131]
	v_pk_mul_f32 v[20:21], v[20:21], v[134:135]
	v_pk_mul_f32 v[30:31], v[30:31], v[128:129]
	v_pk_mul_f32 v[26:27], v[26:27], v[132:133]
	v_pk_mul_f32 v[22:23], v[22:23], v[136:137]
	v_pk_mul_f32 v[18:19], v[18:19], v[146:147]
	v_pk_mul_f32 v[16:17], v[16:17], v[144:145]
	v_pk_mul_f32 v[12:13], v[12:13], v[126:127]
	v_pk_mul_f32 v[8:9], v[8:9], v[130:131]
	v_pk_mul_f32 v[4:5], v[4:5], v[134:135]
	v_pk_mul_f32 v[14:15], v[14:15], v[128:129]
	v_pk_mul_f32 v[10:11], v[10:11], v[132:133]
	v_pk_mul_f32 v[6:7], v[6:7], v[136:137]
	v_pk_mul_f32 v[2:3], v[2:3], v[146:147]
	v_pk_mul_f32 v[0:1], v[0:1], v[144:145]
; __device__ __forceinline__ void partialSM(f32x16& p0, f32x16& p1, float& m_reg, float& mn, float& alpha, const float C, const float thr) {
;     ...
;     const float mnC = -mn * C;
; #pragma unroll
;     for (int r = 0; r < 16; ++r) p0[r] = fmaf(p0[r], C, mnC);
; #pragma unroll
;     for (int r = 0; r < 16; ++r) p1[r] = fmaf(p1[r], C, mnC);
; #pragma unroll
;     for (int r = 0; r < 16; ++r) p0[r] = __builtin_amdgcn_exp2f(p0[r]);
; }
; __device__ __forceinline__ void finishSM(f32x16& p0, f32x16& p1, float alpha, float& l_reg, bf16x8& pa0, bf16x8& pa1, bf16x8& pa2, bf16x8& pa3) {
; #pragma unroll
;     for (int r = 0; r < 16; ++r) p1[r] = __builtin_amdgcn_exp2f(p1[r]);
;     float ps = 0;
; #pragma unroll
;     for (int r = 0; r < 16; ++r) ps += p0[r];
; #pragma unroll
;     for (int r = 0; r < 16; ++r) ps += p1[r];
;     { auto rr = __builtin_amdgcn_permlane32_swap(__float_as_uint(ps), __float_as_uint(ps), false, false);
;       ps = __uint_as_float(rr[0]) + __uint_as_float(rr[1]); }
;     l_reg = l_reg * alpha + ps;
.LBB0_181:
	v_cndmask_b32_e64 v142, v238, v202, s[14:15]
	v_mul_f32_e32 v132, 0xbe38aa3b, v142
	v_mov_b32_e32 v133, v132
	v_fmac_f32_e32 v133, 0x3e38aa3b, v95
	v_exp_f32_e32 v217, v80
	v_exp_f32_e32 v219, v81
	v_exp_f32_e32 v208, v82
	v_exp_f32_e32 v218, v83
	v_exp_f32_e32 v153, v84
	v_exp_f32_e32 v216, v85
	v_exp_f32_e32 v152, v86
	v_exp_f32_e32 v202, v87
	v_exp_f32_e32 v149, v88
	v_exp_f32_e32 v151, v89
	v_exp_f32_e32 v147, v90
	v_exp_f32_e32 v150, v91
	v_exp_f32_e32 v145, v92
	v_exp_f32_e32 v148, v93
	v_exp_f32_e32 v144, v94
	v_exp_f32_e32 v146, v133
	v_pk_fma_f32 v[138:139], v[64:65], s[8:9], v[132:133] op_sel_hi:[1,0,0]
	v_add_f32_e32 v64, v196, v198
	v_fmac_f32_e32 v64, v194, v178
	v_add_f32_e32 v178, v204, v206
	s_add_i32 s52, s52, 2
	v_pk_fma_f32 v[136:137], v[66:67], s[8:9], v[132:133] op_sel_hi:[1,0,0]
	v_pk_fma_f32 v[130:131], v[68:69], s[8:9], v[132:133] op_sel_hi:[1,0,0]
	v_pk_fma_f32 v[128:129], v[70:71], s[8:9], v[132:133] op_sel_hi:[1,0,0]
	v_pk_fma_f32 v[126:127], v[72:73], s[8:9], v[132:133] op_sel_hi:[1,0,0]
	v_pk_fma_f32 v[140:141], v[74:75], s[8:9], v[132:133] op_sel_hi:[1,0,0]
	v_pk_fma_f32 v[134:135], v[76:77], s[8:9], v[132:133] op_sel_hi:[1,0,0]
	v_pk_fma_f32 v[132:133], v[78:79], s[8:9], v[132:133] op_sel_hi:[1,0,0]
	v_fmac_f32_e32 v178, v64, v200
	s_cmp_gt_u32 s37, 32
	s_waitcnt lgkmcnt(0)
	s_barrier
	s_cbranch_scc1 .LBB0_183
	v_mov_b32_e32 v194, v143
	s_branch .LBB0_171
